# remove 3 spurious vmcnt(0) drains per unit in in-proj GEMM
# baseline (speedup 1.0000x reference)
.LBB0_200:
	v_fmamk_f32 v158, v148, 0x3a000000, v203
	s_mov_b32 s29, 0x800000
	v_cmp_gt_f32_e32 vcc, s29, v158
	v_mul_f32_e32 v159, 0x4b800000, v158
	v_lshl_or_b32 v142, s38, 8, v146
	v_cndmask_b32_e32 v158, v158, v159, vcc
	v_rsq_f32_e32 v158, v158
	v_mul_lo_u32 v141, s14, v141
	v_mad_u64_u32 v[156:157], s[4:5], s14, v140, 0
	v_mul_f32_e32 v159, 0x45800000, v158
	v_ashrrev_i32_e32 v143, 31, v142
	v_add_u32_e32 v157, v157, v141
	v_cndmask_b32_e32 v158, v158, v159, vcc
	v_lshl_add_u64 v[156:157], v[156:157], 1, s[18:19]
	v_lshlrev_b64 v[142:143], 1, v[142:143]
	v_cndmask_b32_e64 v158, v158, 1.0, s[24:25]
	v_lshl_add_u64 v[156:157], v[156:157], 0, v[142:143]
	v_pk_mul_f32 v[128:129], v[158:159], v[128:129] op_sel_hi:[0,1]
	v_pk_mul_f32 v[126:127], v[158:159], v[126:127] op_sel_hi:[0,1]
	v_pk_mul_f32 v[160:161], v[158:159], v[124:125] op_sel_hi:[0,1]
	v_pk_mul_f32 v[124:125], v[158:159], v[122:123] op_sel_hi:[0,1]
	v_cvt_pk_bf16_f32 v122, v126, v127
	v_cvt_pk_bf16_f32 v123, v128, v129
	v_cvt_pk_bf16_f32 v124, v124, v125
	v_cvt_pk_bf16_f32 v125, v160, v161
	global_store_dwordx4 v[156:157], v[122:125], off
	v_pk_mul_f32 v[120:121], v[158:159], v[120:121] op_sel_hi:[0,1]
	v_pk_mul_f32 v[118:119], v[158:159], v[118:119] op_sel_hi:[0,1]
	v_pk_mul_f32 v[122:123], v[158:159], v[116:117] op_sel_hi:[0,1]
	v_pk_mul_f32 v[116:117], v[158:159], v[114:115] op_sel_hi:[0,1]
	v_cvt_pk_bf16_f32 v114, v118, v119
	v_cvt_pk_bf16_f32 v115, v120, v121
	v_cvt_pk_bf16_f32 v116, v116, v117
	v_cvt_pk_bf16_f32 v117, v122, v123
	global_store_dwordx4 v[156:157], v[114:117], off offset:256
	s_mov_b32 s38, s28
	s_mov_b64 s[42:43], s[36:37]
	v_fmamk_f32 v116, v150, 0x3a000000, v203
	v_cmp_gt_f32_e32 vcc, s29, v116
	v_mul_f32_e32 v117, 0x4b800000, v116
	v_or_b32_e32 v114, 16, v140
	v_cndmask_b32_e32 v116, v116, v117, vcc
	v_rsq_f32_e32 v116, v116
	v_mad_u64_u32 v[114:115], s[4:5], s14, v114, 0
	v_add_u32_e32 v115, v115, v141
	v_mul_f32_e32 v117, 0x45800000, v116
	v_cndmask_b32_e32 v116, v116, v117, vcc
	v_lshl_add_u64 v[114:115], v[114:115], 1, s[18:19]
	v_cndmask_b32_e64 v116, v116, 1.0, s[24:25]
	v_lshl_add_u64 v[114:115], v[114:115], 0, v[142:143]
	v_pk_mul_f32 v[112:113], v[116:117], v[112:113] op_sel_hi:[0,1]
	v_pk_mul_f32 v[110:111], v[116:117], v[110:111] op_sel_hi:[0,1]
	v_pk_mul_f32 v[118:119], v[116:117], v[108:109] op_sel_hi:[0,1]
	v_pk_mul_f32 v[108:109], v[116:117], v[106:107] op_sel_hi:[0,1]
	v_cvt_pk_bf16_f32 v106, v110, v111
	v_cvt_pk_bf16_f32 v107, v112, v113
	v_cvt_pk_bf16_f32 v108, v108, v109
	v_cvt_pk_bf16_f32 v109, v118, v119
	global_store_dwordx4 v[114:115], v[106:109], off
	v_pk_mul_f32 v[104:105], v[116:117], v[104:105] op_sel_hi:[0,1]
	v_pk_mul_f32 v[102:103], v[116:117], v[102:103] op_sel_hi:[0,1]
	v_pk_mul_f32 v[106:107], v[116:117], v[100:101] op_sel_hi:[0,1]
	v_pk_mul_f32 v[100:101], v[116:117], v[98:99] op_sel_hi:[0,1]
	v_cvt_pk_bf16_f32 v98, v102, v103
	v_cvt_pk_bf16_f32 v99, v104, v105
	v_cvt_pk_bf16_f32 v100, v100, v101
	v_cvt_pk_bf16_f32 v101, v106, v107
	global_store_dwordx4 v[114:115], v[98:101], off offset:256
	s_mov_b64 s[40:41], s[34:35]
	s_nop 0
	v_fmamk_f32 v100, v149, 0x3a000000, v203
	v_cmp_gt_f32_e32 vcc, s29, v100
	v_mul_f32_e32 v101, 0x4b800000, v100
	v_or_b32_e32 v98, 32, v140
	v_cndmask_b32_e32 v100, v100, v101, vcc
	v_rsq_f32_e32 v100, v100
	v_mad_u64_u32 v[98:99], s[4:5], s14, v98, 0
	v_add_u32_e32 v99, v99, v141
	v_mul_f32_e32 v101, 0x45800000, v100
	v_cndmask_b32_e32 v100, v100, v101, vcc
	v_lshl_add_u64 v[98:99], v[98:99], 1, s[18:19]
	v_cndmask_b32_e64 v100, v100, 1.0, s[24:25]
	v_lshl_add_u64 v[98:99], v[98:99], 0, v[142:143]
	v_pk_mul_f32 v[96:97], v[100:101], v[96:97] op_sel_hi:[0,1]
	v_pk_mul_f32 v[94:95], v[100:101], v[94:95] op_sel_hi:[0,1]
	v_pk_mul_f32 v[102:103], v[100:101], v[92:93] op_sel_hi:[0,1]
	v_pk_mul_f32 v[92:93], v[100:101], v[90:91] op_sel_hi:[0,1]
	v_cvt_pk_bf16_f32 v90, v94, v95
	v_cvt_pk_bf16_f32 v91, v96, v97
	v_cvt_pk_bf16_f32 v92, v92, v93
	v_cvt_pk_bf16_f32 v93, v102, v103
	global_store_dwordx4 v[98:99], v[90:93], off
	v_pk_mul_f32 v[88:89], v[100:101], v[88:89] op_sel_hi:[0,1]
	v_pk_mul_f32 v[86:87], v[100:101], v[86:87] op_sel_hi:[0,1]
	v_pk_mul_f32 v[90:91], v[100:101], v[84:85] op_sel_hi:[0,1]
	v_pk_mul_f32 v[84:85], v[100:101], v[82:83] op_sel_hi:[0,1]
	v_cvt_pk_bf16_f32 v82, v86, v87
	v_cvt_pk_bf16_f32 v83, v88, v89
	v_cvt_pk_bf16_f32 v84, v84, v85
	v_cvt_pk_bf16_f32 v85, v90, v91
	global_store_dwordx4 v[98:99], v[82:85], off offset:256
	s_nop 1
	v_fmamk_f32 v84, v151, 0x3a000000, v203
	v_cmp_gt_f32_e32 vcc, s29, v84
	v_mul_f32_e32 v85, 0x4b800000, v84
	v_or_b32_e32 v82, 48, v140
	v_cndmask_b32_e32 v84, v84, v85, vcc
	v_rsq_f32_e32 v84, v84
	v_mad_u64_u32 v[82:83], s[4:5], s14, v82, 0
	v_add_u32_e32 v83, v83, v141
	v_mul_f32_e32 v85, 0x45800000, v84
	v_cndmask_b32_e32 v84, v84, v85, vcc
	v_lshl_add_u64 v[82:83], v[82:83], 1, s[18:19]
	v_cndmask_b32_e64 v84, v84, 1.0, s[24:25]
	v_lshl_add_u64 v[82:83], v[82:83], 0, v[142:143]
	v_pk_mul_f32 v[80:81], v[84:85], v[80:81] op_sel_hi:[0,1]
	v_pk_mul_f32 v[78:79], v[84:85], v[78:79] op_sel_hi:[0,1]
	v_pk_mul_f32 v[86:87], v[84:85], v[76:77] op_sel_hi:[0,1]
	v_pk_mul_f32 v[76:77], v[84:85], v[74:75] op_sel_hi:[0,1]
	v_cvt_pk_bf16_f32 v74, v78, v79
	v_cvt_pk_bf16_f32 v75, v80, v81
	v_cvt_pk_bf16_f32 v76, v76, v77
	v_cvt_pk_bf16_f32 v77, v86, v87
	global_store_dwordx4 v[82:83], v[74:77], off
	v_pk_mul_f32 v[70:71], v[84:85], v[70:71] op_sel_hi:[0,1]
	v_pk_mul_f32 v[72:73], v[84:85], v[72:73] op_sel_hi:[0,1]
	v_pk_mul_f32 v[74:75], v[84:85], v[68:69] op_sel_hi:[0,1]
	v_pk_mul_f32 v[68:69], v[84:85], v[66:67] op_sel_hi:[0,1]
	v_cvt_pk_bf16_f32 v66, v70, v71
	v_cvt_pk_bf16_f32 v67, v72, v73
	v_cvt_pk_bf16_f32 v68, v68, v69
	v_cvt_pk_bf16_f32 v69, v74, v75
	global_store_dwordx4 v[82:83], v[66:69], off offset:256
	s_nop 1
	v_add_u32_e32 v66, 0x80, v140
	v_ashrrev_i32_e32 v69, 31, v66
	v_mad_u64_u32 v[66:67], s[4:5], s14, v66, 0
	v_mov_b32_e32 v68, v67
	v_mad_u64_u32 v[68:69], s[4:5], s14, v69, v[68:69]
	v_mov_b32_e32 v67, v68
	v_fmamk_f32 v68, v152, 0x3a000000, v203
	v_cmp_gt_f32_e32 vcc, s29, v68
	v_mul_f32_e32 v69, 0x4b800000, v68
	v_lshl_add_u64 v[66:67], v[66:67], 1, s[18:19]
	v_cndmask_b32_e32 v68, v68, v69, vcc
	v_rsq_f32_e32 v68, v68
	v_lshl_add_u64 v[66:67], v[66:67], 0, v[142:143]
	v_mul_f32_e32 v69, 0x45800000, v68
	v_cndmask_b32_e32 v68, v68, v69, vcc
	v_cndmask_b32_e64 v68, v68, 1.0, s[24:25]
	v_pk_mul_f32 v[64:65], v[68:69], v[64:65] op_sel_hi:[0,1]
	v_pk_mul_f32 v[62:63], v[68:69], v[62:63] op_sel_hi:[0,1]
	v_pk_mul_f32 v[70:71], v[68:69], v[60:61] op_sel_hi:[0,1]
	v_pk_mul_f32 v[60:61], v[68:69], v[58:59] op_sel_hi:[0,1]
	v_cvt_pk_bf16_f32 v58, v62, v63
	v_cvt_pk_bf16_f32 v59, v64, v65
	v_cvt_pk_bf16_f32 v60, v60, v61
	v_cvt_pk_bf16_f32 v61, v70, v71
	global_store_dwordx4 v[66:67], v[58:61], off
	v_pk_mul_f32 v[54:55], v[68:69], v[54:55] op_sel_hi:[0,1]
	v_pk_mul_f32 v[56:57], v[68:69], v[56:57] op_sel_hi:[0,1]
	v_pk_mul_f32 v[58:59], v[68:69], v[52:53] op_sel_hi:[0,1]
	v_pk_mul_f32 v[52:53], v[68:69], v[50:51] op_sel_hi:[0,1]
	v_cvt_pk_bf16_f32 v50, v54, v55
	v_cvt_pk_bf16_f32 v51, v56, v57
	v_cvt_pk_bf16_f32 v52, v52, v53
	v_cvt_pk_bf16_f32 v53, v58, v59
	global_store_dwordx4 v[66:67], v[50:53], off offset:256
	s_nop 1
	v_add_u32_e32 v50, 0x90, v140
	v_ashrrev_i32_e32 v53, 31, v50
	v_mad_u64_u32 v[50:51], s[4:5], s14, v50, 0
	v_mov_b32_e32 v52, v51
	v_mad_u64_u32 v[52:53], s[4:5], s14, v53, v[52:53]
	v_mov_b32_e32 v51, v52
	v_fmamk_f32 v52, v154, 0x3a000000, v203
	v_cmp_gt_f32_e32 vcc, s29, v52
	v_mul_f32_e32 v53, 0x4b800000, v52
	v_lshl_add_u64 v[50:51], v[50:51], 1, s[18:19]
	v_cndmask_b32_e32 v52, v52, v53, vcc
	v_rsq_f32_e32 v52, v52
	v_lshl_add_u64 v[50:51], v[50:51], 0, v[142:143]
	v_mul_f32_e32 v53, 0x45800000, v52
	v_cndmask_b32_e32 v52, v52, v53, vcc
	v_cndmask_b32_e64 v52, v52, 1.0, s[24:25]
	v_pk_mul_f32 v[48:49], v[52:53], v[48:49] op_sel_hi:[0,1]
	v_pk_mul_f32 v[46:47], v[52:53], v[46:47] op_sel_hi:[0,1]
	v_pk_mul_f32 v[54:55], v[52:53], v[44:45] op_sel_hi:[0,1]
	v_pk_mul_f32 v[44:45], v[52:53], v[42:43] op_sel_hi:[0,1]
	v_cvt_pk_bf16_f32 v42, v46, v47
	v_cvt_pk_bf16_f32 v43, v48, v49
	v_cvt_pk_bf16_f32 v44, v44, v45
	v_cvt_pk_bf16_f32 v45, v54, v55
	global_store_dwordx4 v[50:51], v[42:45], off
	v_pk_mul_f32 v[38:39], v[52:53], v[38:39] op_sel_hi:[0,1]
	v_pk_mul_f32 v[40:41], v[52:53], v[40:41] op_sel_hi:[0,1]
	v_pk_mul_f32 v[42:43], v[52:53], v[36:37] op_sel_hi:[0,1]
	v_pk_mul_f32 v[36:37], v[52:53], v[34:35] op_sel_hi:[0,1]
	v_cvt_pk_bf16_f32 v34, v38, v39
	v_cvt_pk_bf16_f32 v35, v40, v41
	v_cvt_pk_bf16_f32 v36, v36, v37
	v_cvt_pk_bf16_f32 v37, v42, v43
	global_store_dwordx4 v[50:51], v[34:37], off offset:256
	s_nop 1
	v_add_u32_e32 v34, 0xa0, v140
	v_ashrrev_i32_e32 v37, 31, v34
	v_mad_u64_u32 v[34:35], s[4:5], s14, v34, 0
	v_mov_b32_e32 v36, v35
	v_mad_u64_u32 v[36:37], s[4:5], s14, v37, v[36:37]
	v_mov_b32_e32 v35, v36
	v_fmamk_f32 v36, v155, 0x3a000000, v203
	v_cmp_gt_f32_e32 vcc, s29, v36
	v_mul_f32_e32 v37, 0x4b800000, v36
	v_lshl_add_u64 v[34:35], v[34:35], 1, s[18:19]
	v_cndmask_b32_e32 v36, v36, v37, vcc
	v_rsq_f32_e32 v36, v36
	v_lshl_add_u64 v[34:35], v[34:35], 0, v[142:143]
	v_mul_f32_e32 v37, 0x45800000, v36
	v_cndmask_b32_e32 v36, v36, v37, vcc
	v_cndmask_b32_e64 v36, v36, 1.0, s[24:25]
	v_pk_mul_f32 v[32:33], v[36:37], v[32:33] op_sel_hi:[0,1]
	v_pk_mul_f32 v[30:31], v[36:37], v[30:31] op_sel_hi:[0,1]
	v_pk_mul_f32 v[38:39], v[36:37], v[28:29] op_sel_hi:[0,1]
	v_pk_mul_f32 v[28:29], v[36:37], v[26:27] op_sel_hi:[0,1]
	v_cvt_pk_bf16_f32 v26, v30, v31
	v_cvt_pk_bf16_f32 v27, v32, v33
	v_cvt_pk_bf16_f32 v28, v28, v29
	v_cvt_pk_bf16_f32 v29, v38, v39
	global_store_dwordx4 v[34:35], v[26:29], off
	v_pk_mul_f32 v[22:23], v[36:37], v[22:23] op_sel_hi:[0,1]
	v_pk_mul_f32 v[24:25], v[36:37], v[24:25] op_sel_hi:[0,1]
	v_pk_mul_f32 v[26:27], v[36:37], v[20:21] op_sel_hi:[0,1]
	v_pk_mul_f32 v[20:21], v[36:37], v[18:19] op_sel_hi:[0,1]
	v_cvt_pk_bf16_f32 v18, v22, v23
	v_cvt_pk_bf16_f32 v19, v24, v25
	v_cvt_pk_bf16_f32 v20, v20, v21
	v_cvt_pk_bf16_f32 v21, v26, v27
	global_store_dwordx4 v[34:35], v[18:21], off offset:256
	s_nop 1
	v_fmamk_f32 v18, v153, 0x3a000000, v203
	v_cmp_gt_f32_e32 vcc, s29, v18
	v_mul_f32_e32 v19, 0x4b800000, v18
	s_nop 0
	v_cndmask_b32_e32 v18, v18, v19, vcc
	v_rsq_f32_e32 v18, v18
	s_nop 0
	v_mul_f32_e32 v19, 0x45800000, v18
	v_cndmask_b32_e32 v18, v18, v19, vcc
	v_add_u32_e32 v19, 0xb0, v140
	v_mad_u64_u32 v[20:21], s[4:5], s14, v19, 0
	v_ashrrev_i32_e32 v23, 31, v19
	v_mov_b32_e32 v22, v21
	v_mad_u64_u32 v[22:23], s[4:5], s14, v23, v[22:23]
	v_mov_b32_e32 v21, v22
	v_cndmask_b32_e64 v18, v18, 1.0, s[24:25]
	v_lshl_add_u64 v[20:21], v[20:21], 1, s[18:19]
	v_lshl_add_u64 v[20:21], v[20:21], 0, v[142:143]
	v_pk_mul_f32 v[16:17], v[18:19], v[16:17] op_sel_hi:[0,1]
	v_pk_mul_f32 v[14:15], v[18:19], v[14:15] op_sel_hi:[0,1]
	v_pk_mul_f32 v[22:23], v[18:19], v[12:13] op_sel_hi:[0,1]
	v_pk_mul_f32 v[12:13], v[18:19], v[10:11] op_sel_hi:[0,1]
	v_cvt_pk_bf16_f32 v10, v14, v15
	v_cvt_pk_bf16_f32 v11, v16, v17
	v_cvt_pk_bf16_f32 v12, v12, v13
	v_cvt_pk_bf16_f32 v13, v22, v23
	global_store_dwordx4 v[20:21], v[10:13], off
	s_and_b64 vcc, exec, s[0:1]
	s_mov_b32 s4, s30
	v_pk_mul_f32 v[10:11], v[18:19], v[4:5] op_sel_hi:[0,1]
	v_pk_mul_f32 v[4:5], v[18:19], v[2:3] op_sel_hi:[0,1]
	v_pk_mul_f32 v[8:9], v[18:19], v[8:9] op_sel_hi:[0,1]
	v_pk_mul_f32 v[6:7], v[18:19], v[6:7] op_sel_hi:[0,1]
	v_cvt_pk_bf16_f32 v2, v6, v7
	v_cvt_pk_bf16_f32 v3, v8, v9
	v_cvt_pk_bf16_f32 v4, v4, v5
	v_cvt_pk_bf16_f32 v5, v10, v11
	global_store_dwordx4 v[20:21], v[2:5], off offset:256
	s_cbranch_vccnz .LBB0_214

.LBB0_203:
	v_mov_b64_e32 v[2:3], s[2:3]
	s_ashr_i32 s31, s30, 31
	v_cmp_lt_i64_e32 vcc, s[34:35], v[2:3]
	s_lshl_b64 s[34:35], s[30:31], 20
	s_add_u32 s34, s20, s34
	s_addc_u32 s35, s21, s35
	s_and_b64 s[36:37], vcc, exec
	s_cselect_b32 s31, s35, s41
	s_cselect_b32 s65, s34, s40
	s_ashr_i32 s29, s28, 31
	s_lshl_b64 s[36:37], s[28:29], 20
	s_add_u32 s36, s22, s36
	s_addc_u32 s37, s23, s37
	s_and_b64 s[44:45], vcc, exec
	s_cselect_b32 s29, s37, s43
	s_cselect_b32 s66, s36, s42
	s_add_u32 s40, s40, 0x80080
	v_lshl_add_u32 v140, s4, 8, v144
	s_addc_u32 s41, s41, 0
	v_ashrrev_i32_e32 v141, 31, v140
	s_add_u32 s67, s42, 0x100
	v_mov_b32_e32 v2, 0
	v_lshl_add_u64 v[142:143], v[140:141], 2, s[16:17]
	s_addc_u32 s68, s43, 0
	s_mov_b32 s69, -2
	v_mov_b32_e32 v3, v2
	v_mov_b32_e32 v4, v2
	v_mov_b32_e32 v5, v2
	v_mov_b32_e32 v6, v2
	v_mov_b32_e32 v7, v2
	v_mov_b32_e32 v8, v2
	v_mov_b32_e32 v9, v2
	v_mov_b32_e32 v18, v2
	v_mov_b32_e32 v19, v2
	v_mov_b32_e32 v20, v2
	v_mov_b32_e32 v21, v2
	v_mov_b32_e32 v22, v2
	v_mov_b32_e32 v23, v2
	v_mov_b32_e32 v24, v2
	v_mov_b32_e32 v25, v2
	v_mov_b32_e32 v34, v2
	v_mov_b32_e32 v35, v2
	v_mov_b32_e32 v36, v2
	v_mov_b32_e32 v37, v2
	v_mov_b32_e32 v38, v2
	v_mov_b32_e32 v39, v2
	v_mov_b32_e32 v40, v2
	v_mov_b32_e32 v41, v2
	v_mov_b32_e32 v50, v2
	v_mov_b32_e32 v51, v2
	v_mov_b32_e32 v52, v2
	v_mov_b32_e32 v53, v2
	v_mov_b32_e32 v54, v2
	v_mov_b32_e32 v55, v2
	v_mov_b32_e32 v56, v2
	v_mov_b32_e32 v57, v2
	v_mov_b32_e32 v10, v2
	v_mov_b32_e32 v11, v2
	v_mov_b32_e32 v12, v2
	v_mov_b32_e32 v13, v2
	v_mov_b32_e32 v14, v2
	v_mov_b32_e32 v15, v2
	v_mov_b32_e32 v16, v2
	v_mov_b32_e32 v17, v2
	v_mov_b32_e32 v26, v2
	v_mov_b32_e32 v27, v2
	v_mov_b32_e32 v28, v2
	v_mov_b32_e32 v29, v2
	v_mov_b32_e32 v30, v2
	v_mov_b32_e32 v31, v2
	v_mov_b32_e32 v32, v2
	v_mov_b32_e32 v33, v2
	v_mov_b32_e32 v42, v2
	v_mov_b32_e32 v43, v2
	v_mov_b32_e32 v44, v2
	v_mov_b32_e32 v45, v2
	v_mov_b32_e32 v46, v2
	v_mov_b32_e32 v47, v2
	v_mov_b32_e32 v48, v2
	v_mov_b32_e32 v49, v2
	v_mov_b32_e32 v58, v2
	v_mov_b32_e32 v59, v2
	v_mov_b32_e32 v60, v2
	v_mov_b32_e32 v61, v2
	v_mov_b32_e32 v62, v2
	v_mov_b32_e32 v63, v2
	v_mov_b32_e32 v64, v2
	v_mov_b32_e32 v65, v2
	v_mov_b32_e32 v66, v2
	v_mov_b32_e32 v67, v2
	v_mov_b32_e32 v68, v2
	v_mov_b32_e32 v69, v2
	v_mov_b32_e32 v70, v2
	v_mov_b32_e32 v71, v2
	v_mov_b32_e32 v72, v2
	v_mov_b32_e32 v73, v2
	v_mov_b32_e32 v82, v2
	v_mov_b32_e32 v83, v2
	v_mov_b32_e32 v84, v2
	v_mov_b32_e32 v85, v2
	v_mov_b32_e32 v86, v2
	v_mov_b32_e32 v87, v2
	v_mov_b32_e32 v88, v2
	v_mov_b32_e32 v89, v2
	v_mov_b32_e32 v98, v2
	v_mov_b32_e32 v99, v2
	v_mov_b32_e32 v100, v2
	v_mov_b32_e32 v101, v2
	v_mov_b32_e32 v102, v2
	v_mov_b32_e32 v103, v2
	v_mov_b32_e32 v104, v2
	v_mov_b32_e32 v105, v2
	v_mov_b32_e32 v114, v2
	v_mov_b32_e32 v115, v2
	v_mov_b32_e32 v116, v2
	v_mov_b32_e32 v117, v2
	v_mov_b32_e32 v118, v2
	v_mov_b32_e32 v119, v2
	v_mov_b32_e32 v120, v2
	v_mov_b32_e32 v121, v2
	v_mov_b32_e32 v74, v2
	v_mov_b32_e32 v75, v2
	v_mov_b32_e32 v76, v2
	v_mov_b32_e32 v77, v2
	v_mov_b32_e32 v78, v2
	v_mov_b32_e32 v79, v2
	v_mov_b32_e32 v80, v2
	v_mov_b32_e32 v81, v2
	v_mov_b32_e32 v90, v2
	v_mov_b32_e32 v91, v2
	v_mov_b32_e32 v92, v2
	v_mov_b32_e32 v93, v2
	v_mov_b32_e32 v94, v2
	v_mov_b32_e32 v95, v2
	v_mov_b32_e32 v96, v2
	v_mov_b32_e32 v97, v2
	v_mov_b32_e32 v106, v2
	v_mov_b32_e32 v107, v2
	v_mov_b32_e32 v108, v2
	v_mov_b32_e32 v109, v2
	v_mov_b32_e32 v110, v2
	v_mov_b32_e32 v111, v2
	v_mov_b32_e32 v112, v2
	v_mov_b32_e32 v113, v2
	v_mov_b32_e32 v122, v2
	v_mov_b32_e32 v123, v2
	v_mov_b32_e32 v124, v2
	v_mov_b32_e32 v125, v2
	v_mov_b32_e32 v126, v2
	v_mov_b32_e32 v127, v2
	v_mov_b32_e32 v128, v2
	v_mov_b32_e32 v129, v2
	s_branch .LBB0_205

.LBB0_205:
	s_cmp_eq_u32 s69, 28
	s_cselect_b64 s[42:43], -1, 0
	s_cmp_lg_u32 s69, 28
	s_cbranch_scc1 .LBB0_204
	v_cndmask_b32_e64 v148, 0, 1, s[26:27]
	v_mov_b32_e32 v149, 0
	v_cmp_ne_u32_e64 s[4:5], 1, v148
	s_andn2_b64 vcc, exec, s[26:27]
	v_mov_b32_e32 v148, 0
	v_mov_b32_e32 v150, 0
	s_cbranch_vccnz .LBB0_208
	global_load_dword v148, v[142:143], off
	global_load_dword v150, v[142:143], off offset:64
